# norm_phase gate-weight staging loop (16 serialized load-wait-mul-store rounds) fully unrolled with all 32 loads issued up front, both instances
# speedup vs baseline: 1.0018x; 1.0018x over previous
; template <bool BIN, bool WRITE_U> __device__ __forceinline__ void norm_phase(const void* hin_, const float* gain, bf16* U, const float* Wg, int ldw, int goff, int ng, float* GATE, float* RSTD, unsigned char* lds) {
;     ...
;         for (int idx = tid; idx < 1024 * 8; idx += 512) { const int k = idx >> 3, g = idx & 7; wl[idx] = (g < ng) ? Wg[(size_t)k * ldw + goff + g] * gain[k] : 0.f; }
.LBB0_185:
	v_mov_b32_e32 v200, 0
	v_mov_b32_e32 v201, 0
	v_mov_b32_e32 v202, 0
	v_mov_b32_e32 v203, 0
	v_mov_b32_e32 v204, 0
	v_mov_b32_e32 v205, 0
	v_mov_b32_e32 v206, 0
	v_mov_b32_e32 v207, 0
	v_mov_b32_e32 v208, 0
	v_mov_b32_e32 v209, 0
	v_mov_b32_e32 v210, 0
	v_mov_b32_e32 v211, 0
	v_mov_b32_e32 v212, 0
	v_mov_b32_e32 v213, 0
	v_mov_b32_e32 v214, 0
	v_mov_b32_e32 v215, 0
	s_and_saveexec_b64 s[4:5], vcc
	s_cbranch_execz .Lnpwa_st
	v_ashrrev_i32_e32 v6, 3, v4
	v_ashrrev_i32_e32 v7, 31, v6
	v_mad_i64_i32 v[8:9], s[18:19], s26, v6, 0
	v_lshl_add_u64 v[8:9], v[8:9], 2, v[2:3]
	v_lshl_add_u64 v[6:7], v[6:7], 2, s[10:11]
	s_lshl_b32 s18, s26, 8
	s_mov_b32 s19, 0
	global_load_dword v200, v[8:9], off
	global_load_dword v216, v[6:7], off
	v_lshl_add_u64 v[8:9], s[18:19], 0, v[8:9]
	global_load_dword v201, v[8:9], off
	global_load_dword v217, v[6:7], off offset:256
	v_lshl_add_u64 v[8:9], s[18:19], 0, v[8:9]
	global_load_dword v202, v[8:9], off
	global_load_dword v218, v[6:7], off offset:512
	v_lshl_add_u64 v[8:9], s[18:19], 0, v[8:9]
	global_load_dword v203, v[8:9], off
	global_load_dword v219, v[6:7], off offset:768
	v_lshl_add_u64 v[8:9], s[18:19], 0, v[8:9]
	global_load_dword v204, v[8:9], off
	global_load_dword v220, v[6:7], off offset:1024
	v_lshl_add_u64 v[8:9], s[18:19], 0, v[8:9]
	global_load_dword v205, v[8:9], off
	global_load_dword v221, v[6:7], off offset:1280
	v_lshl_add_u64 v[8:9], s[18:19], 0, v[8:9]
	global_load_dword v206, v[8:9], off
	global_load_dword v222, v[6:7], off offset:1536
	v_lshl_add_u64 v[8:9], s[18:19], 0, v[8:9]
	global_load_dword v207, v[8:9], off
	global_load_dword v223, v[6:7], off offset:1792
	v_lshl_add_u64 v[8:9], s[18:19], 0, v[8:9]
	global_load_dword v208, v[8:9], off
	global_load_dword v239, v[6:7], off offset:2048
	v_lshl_add_u64 v[8:9], s[18:19], 0, v[8:9]
	global_load_dword v209, v[8:9], off
	global_load_dword v240, v[6:7], off offset:2304
	v_lshl_add_u64 v[8:9], s[18:19], 0, v[8:9]
	global_load_dword v210, v[8:9], off
	global_load_dword v241, v[6:7], off offset:2560
	v_lshl_add_u64 v[8:9], s[18:19], 0, v[8:9]
	global_load_dword v211, v[8:9], off
	global_load_dword v242, v[6:7], off offset:2816
	v_lshl_add_u64 v[8:9], s[18:19], 0, v[8:9]
	global_load_dword v212, v[8:9], off
	global_load_dword v243, v[6:7], off offset:3072
	v_lshl_add_u64 v[8:9], s[18:19], 0, v[8:9]
	global_load_dword v213, v[8:9], off
	global_load_dword v244, v[6:7], off offset:3328
	v_lshl_add_u64 v[8:9], s[18:19], 0, v[8:9]
	global_load_dword v214, v[8:9], off
	global_load_dword v245, v[6:7], off offset:3584
	v_lshl_add_u64 v[8:9], s[18:19], 0, v[8:9]
	global_load_dword v215, v[8:9], off
	global_load_dword v246, v[6:7], off offset:3840
	s_waitcnt vmcnt(0)
	v_mul_f32_e32 v200, v200, v216
	v_mul_f32_e32 v201, v201, v217
	v_mul_f32_e32 v202, v202, v218
	v_mul_f32_e32 v203, v203, v219
	v_mul_f32_e32 v204, v204, v220
	v_mul_f32_e32 v205, v205, v221
	v_mul_f32_e32 v206, v206, v222
	v_mul_f32_e32 v207, v207, v223
	v_mul_f32_e32 v208, v208, v239
	v_mul_f32_e32 v209, v209, v240
	v_mul_f32_e32 v210, v210, v241
	v_mul_f32_e32 v211, v211, v242
	v_mul_f32_e32 v212, v212, v243
	v_mul_f32_e32 v213, v213, v244
	v_mul_f32_e32 v214, v214, v245
	v_mul_f32_e32 v215, v215, v246
.Lnpwa_st:
	s_or_b64 exec, exec, s[4:5]
	ds_write_b32 v1, v200
	ds_write_b32 v1, v201 offset:2048
	ds_write_b32 v1, v202 offset:4096
	ds_write_b32 v1, v203 offset:6144
	ds_write_b32 v1, v204 offset:8192
	ds_write_b32 v1, v205 offset:10240
	ds_write_b32 v1, v206 offset:12288
	ds_write_b32 v1, v207 offset:14336
	ds_write_b32 v1, v208 offset:16384
	ds_write_b32 v1, v209 offset:18432
	ds_write_b32 v1, v210 offset:20480
	ds_write_b32 v1, v211 offset:22528
	ds_write_b32 v1, v212 offset:24576
	ds_write_b32 v1, v213 offset:26624
	ds_write_b32 v1, v214 offset:28672
	ds_write_b32 v1, v215 offset:30720

; template <bool BIN, bool WRITE_U> __device__ __forceinline__ void norm_phase(const void* hin_, const float* gain, bf16* U, const float* Wg, int ldw, int goff, int ng, float* GATE, float* RSTD, unsigned char* lds) {
;     ...
;         for (int idx = tid; idx < 1024 * 8; idx += 512) { const int k = idx >> 3, g = idx & 7; wl[idx] = (g < ng) ? Wg[(size_t)k * ldw + goff + g] * gain[k] : 0.f; }
.LBB0_205:
	v_mov_b32_e32 v200, 0
	v_mov_b32_e32 v201, 0
	v_mov_b32_e32 v202, 0
	v_mov_b32_e32 v203, 0
	v_mov_b32_e32 v204, 0
	v_mov_b32_e32 v205, 0
	v_mov_b32_e32 v206, 0
	v_mov_b32_e32 v207, 0
	v_mov_b32_e32 v208, 0
	v_mov_b32_e32 v209, 0
	v_mov_b32_e32 v210, 0
	v_mov_b32_e32 v211, 0
	v_mov_b32_e32 v212, 0
	v_mov_b32_e32 v213, 0
	v_mov_b32_e32 v214, 0
	v_mov_b32_e32 v215, 0
	s_and_saveexec_b64 s[4:5], vcc
	s_cbranch_execz .Lnpwb_st
	v_ashrrev_i32_e32 v6, 3, v4
	v_ashrrev_i32_e32 v7, 31, v6
	v_mad_i64_i32 v[8:9], s[16:17], s26, v6, 0
	v_lshl_add_u64 v[8:9], v[8:9], 2, v[2:3]
	s_waitcnt lgkmcnt(0)
	v_lshl_add_u64 v[6:7], v[6:7], 2, s[10:11]
	s_lshl_b32 s16, s26, 8
	s_mov_b32 s17, 0
	global_load_dword v200, v[8:9], off
	global_load_dword v216, v[6:7], off
	v_lshl_add_u64 v[8:9], s[16:17], 0, v[8:9]
	global_load_dword v201, v[8:9], off
	global_load_dword v217, v[6:7], off offset:256
	v_lshl_add_u64 v[8:9], s[16:17], 0, v[8:9]
	global_load_dword v202, v[8:9], off
	global_load_dword v218, v[6:7], off offset:512
	v_lshl_add_u64 v[8:9], s[16:17], 0, v[8:9]
	global_load_dword v203, v[8:9], off
	global_load_dword v219, v[6:7], off offset:768
	v_lshl_add_u64 v[8:9], s[16:17], 0, v[8:9]
	global_load_dword v204, v[8:9], off
	global_load_dword v220, v[6:7], off offset:1024
	v_lshl_add_u64 v[8:9], s[16:17], 0, v[8:9]
	global_load_dword v205, v[8:9], off
	global_load_dword v221, v[6:7], off offset:1280
	v_lshl_add_u64 v[8:9], s[16:17], 0, v[8:9]
	global_load_dword v206, v[8:9], off
	global_load_dword v222, v[6:7], off offset:1536
	v_lshl_add_u64 v[8:9], s[16:17], 0, v[8:9]
	global_load_dword v207, v[8:9], off
	global_load_dword v223, v[6:7], off offset:1792
	v_lshl_add_u64 v[8:9], s[16:17], 0, v[8:9]
	global_load_dword v208, v[8:9], off
	global_load_dword v239, v[6:7], off offset:2048
	v_lshl_add_u64 v[8:9], s[16:17], 0, v[8:9]
	global_load_dword v209, v[8:9], off
	global_load_dword v240, v[6:7], off offset:2304
	v_lshl_add_u64 v[8:9], s[16:17], 0, v[8:9]
	global_load_dword v210, v[8:9], off
	global_load_dword v241, v[6:7], off offset:2560
	v_lshl_add_u64 v[8:9], s[16:17], 0, v[8:9]
	global_load_dword v211, v[8:9], off
	global_load_dword v242, v[6:7], off offset:2816
	v_lshl_add_u64 v[8:9], s[16:17], 0, v[8:9]
	global_load_dword v212, v[8:9], off
	global_load_dword v243, v[6:7], off offset:3072
	v_lshl_add_u64 v[8:9], s[16:17], 0, v[8:9]
	global_load_dword v213, v[8:9], off
	global_load_dword v244, v[6:7], off offset:3328
	v_lshl_add_u64 v[8:9], s[16:17], 0, v[8:9]
	global_load_dword v214, v[8:9], off
	global_load_dword v245, v[6:7], off offset:3584
	v_lshl_add_u64 v[8:9], s[16:17], 0, v[8:9]
	global_load_dword v215, v[8:9], off
	global_load_dword v246, v[6:7], off offset:3840
	s_waitcnt vmcnt(0)
	v_mul_f32_e32 v200, v200, v216
	v_mul_f32_e32 v201, v201, v217
	v_mul_f32_e32 v202, v202, v218
	v_mul_f32_e32 v203, v203, v219
	v_mul_f32_e32 v204, v204, v220
	v_mul_f32_e32 v205, v205, v221
	v_mul_f32_e32 v206, v206, v222
	v_mul_f32_e32 v207, v207, v223
	v_mul_f32_e32 v208, v208, v239
	v_mul_f32_e32 v209, v209, v240
	v_mul_f32_e32 v210, v210, v241
	v_mul_f32_e32 v211, v211, v242
	v_mul_f32_e32 v212, v212, v243
	v_mul_f32_e32 v213, v213, v244
	v_mul_f32_e32 v214, v214, v245
	v_mul_f32_e32 v215, v215, v246
